# speedup vs baseline: 1.0424x; 1.0132x over previous
.LBB0_481:
	v_max_f32_e32 v0, v81, v81
	v_max_f32_e32 v14, v80, v80
	v_max_f32_e32 v0, v14, v0
	v_max3_f32 v0, v0, v82, v83
	v_max3_f32 v0, v0, v84, v85
	v_max3_f32 v0, v0, v86, v87
	v_max3_f32 v0, v0, v88, v89
	v_max3_f32 v0, v0, v90, v91
	v_max3_f32 v0, v0, v92, v93
	v_max3_f32 v0, v0, v94, v95
	v_max3_f32 v0, v0, v96, v97
	v_max3_f32 v0, v0, v98, v99
	v_max3_f32 v0, v0, v100, v101
	v_max3_f32 v0, v0, v102, v103
	v_max3_f32 v0, v0, v104, v105
	v_max3_f32 v0, v0, v106, v107
	v_max3_f32 v0, v0, v108, v109
	v_max3_f32 v0, v0, v110, v111
	v_mov_b32_e32 v14, v0
	v_mov_b32_e32 v15, v0
	s_nop 1
	v_permlane32_swap_b32_e32 v14, v15
	v_max3_f32 v14, v193, v14, v15
	v_sub_f32_e32 v0, v80, v14
	v_exp_f32_e32 v80, v0
	v_sub_f32_e32 v0, v81, v14
	v_exp_f32_e32 v81, v0
	v_sub_f32_e32 v0, v193, v14
	v_sub_f32_e32 v82, v82, v14
	v_sub_f32_e32 v83, v83, v14
	v_sub_f32_e32 v84, v84, v14
	v_sub_f32_e32 v85, v85, v14
	v_sub_f32_e32 v86, v86, v14
	v_sub_f32_e32 v87, v87, v14
	v_add_u32_e32 v193, v191, v192
	v_exp_f32_e32 v82, v82
	v_exp_f32_e32 v83, v83
	v_exp_f32_e32 v84, v84
	v_exp_f32_e32 v85, v85
	v_exp_f32_e32 v86, v86
	v_exp_f32_e32 v87, v87
	v_exp_f32_e32 v0, v0
	ds_read_b64_tr_b16 v[194:195], v193 offset:38912
	ds_read_b64_tr_b16 v[196:197], v193 offset:40448
	ds_read_b64_tr_b16 v[204:205], v193 offset:40512
	ds_read_b64_tr_b16 v[202:203], v193 offset:38976
	v_add_f32_e32 v15, 0, v80
	v_add_f32_e32 v15, v81, v15
	v_cmp_neq_f32_e32 vcc, 1.0, v0
	s_cbranch_vccz .Lnoresc_B
	v_mul_f32_e32 v30, v0, v30
	v_mul_f32_e32 v31, v0, v31
	v_mul_f32_e32 v28, v0, v28
	v_mul_f32_e32 v29, v0, v29
	v_mul_f32_e32 v26, v0, v26
	v_mul_f32_e32 v27, v0, v27
	v_mul_f32_e32 v24, v0, v24
	v_mul_f32_e32 v25, v0, v25
	v_mul_f32_e32 v22, v0, v22
	v_mul_f32_e32 v23, v0, v23
	v_mul_f32_e32 v20, v0, v20
	v_mul_f32_e32 v21, v0, v21
	v_mul_f32_e32 v18, v0, v18
	v_mul_f32_e32 v19, v0, v19
	v_mul_f32_e32 v16, v0, v16
	v_mul_f32_e32 v17, v0, v17
	v_mul_f32_e32 v46, v0, v46
	v_mul_f32_e32 v47, v0, v47
	v_mul_f32_e32 v44, v0, v44
	v_mul_f32_e32 v45, v0, v45
	v_mul_f32_e32 v42, v0, v42
	v_mul_f32_e32 v43, v0, v43
	v_mul_f32_e32 v40, v0, v40
	v_mul_f32_e32 v41, v0, v41
	v_mul_f32_e32 v38, v0, v38
	v_mul_f32_e32 v39, v0, v39
	v_mul_f32_e32 v36, v0, v36
	v_mul_f32_e32 v37, v0, v37
	v_mul_f32_e32 v34, v0, v34
	v_mul_f32_e32 v35, v0, v35
	v_mul_f32_e32 v32, v0, v32
	v_mul_f32_e32 v33, v0, v33
.Lnoresc_B:
	v_cvt_pk_bf16_f32 v198, v80, v81
	v_cvt_pk_bf16_f32 v199, v82, v83
	v_cvt_pk_bf16_f32 v200, v84, v85
	v_cvt_pk_bf16_f32 v201, v86, v87
	v_add_f32_e32 v15, v82, v15
	s_waitcnt lgkmcnt(2)
	v_mfma_f32_32x32x16_bf16 v[16:31], v[194:197], v[198:201], v[16:31]
	v_add_f32_e32 v15, v83, v15
	v_sub_f32_e32 v88, v88, v14
	v_add_f32_e32 v15, v84, v15
	v_exp_f32_e32 v88, v88
	v_sub_f32_e32 v89, v89, v14
	v_sub_f32_e32 v90, v90, v14
	v_sub_f32_e32 v91, v91, v14
	s_waitcnt lgkmcnt(0)
	v_mfma_f32_32x32x16_bf16 v[32:47], v[202:205], v[198:201], v[32:47]
	v_sub_f32_e32 v92, v92, v14
	v_sub_f32_e32 v93, v93, v14
	v_sub_f32_e32 v94, v94, v14
	v_sub_f32_e32 v95, v95, v14
	v_add_f32_e32 v15, v85, v15
	v_exp_f32_e32 v89, v89
	v_exp_f32_e32 v90, v90
	v_exp_f32_e32 v91, v91
	v_exp_f32_e32 v92, v92
	v_exp_f32_e32 v93, v93
	v_exp_f32_e32 v94, v94
	v_exp_f32_e32 v95, v95
	ds_read_b64_tr_b16 v[194:195], v193 offset:41984
	ds_read_b64_tr_b16 v[196:197], v193 offset:43520
	ds_read_b64_tr_b16 v[204:205], v193 offset:43584
	ds_read_b64_tr_b16 v[202:203], v193 offset:42048
	v_add_f32_e32 v15, v86, v15
	v_add_f32_e32 v15, v87, v15
	v_add_f32_e32 v15, v88, v15
	v_add_f32_e32 v15, v89, v15
	v_cvt_pk_bf16_f32 v198, v88, v89
	v_cvt_pk_bf16_f32 v199, v90, v91
	v_cvt_pk_bf16_f32 v200, v92, v93
	v_cvt_pk_bf16_f32 v201, v94, v95
	v_add_f32_e32 v15, v90, v15
	v_add_f32_e32 v15, v91, v15
	s_waitcnt lgkmcnt(2)
	v_mfma_f32_32x32x16_bf16 v[16:31], v[194:197], v[198:201], v[16:31]
	v_sub_f32_e32 v96, v96, v14
	v_add_f32_e32 v15, v92, v15
	v_exp_f32_e32 v96, v96
	v_sub_f32_e32 v97, v97, v14
	v_sub_f32_e32 v98, v98, v14
	v_sub_f32_e32 v99, v99, v14
	v_sub_f32_e32 v100, v100, v14
	s_waitcnt lgkmcnt(0)
	v_mfma_f32_32x32x16_bf16 v[32:47], v[202:205], v[198:201], v[32:47]
	v_sub_f32_e32 v101, v101, v14
	v_sub_f32_e32 v102, v102, v14
	v_sub_f32_e32 v103, v103, v14
	v_add_f32_e32 v15, v93, v15
	v_exp_f32_e32 v97, v97
	v_exp_f32_e32 v98, v98
	v_exp_f32_e32 v99, v99
	v_exp_f32_e32 v100, v100
	v_exp_f32_e32 v101, v101
	v_exp_f32_e32 v102, v102
	v_exp_f32_e32 v103, v103
	ds_read_b64_tr_b16 v[194:195], v193 offset:45056
	ds_read_b64_tr_b16 v[196:197], v193 offset:46592
	ds_read_b64_tr_b16 v[204:205], v193 offset:46656
	ds_read_b64_tr_b16 v[202:203], v193 offset:45120
	v_add_f32_e32 v15, v94, v15
	v_add_f32_e32 v15, v95, v15
	v_add_f32_e32 v15, v96, v15
	v_add_f32_e32 v15, v97, v15
	v_cvt_pk_bf16_f32 v198, v96, v97
	v_cvt_pk_bf16_f32 v199, v98, v99
	v_cvt_pk_bf16_f32 v200, v100, v101
	v_cvt_pk_bf16_f32 v201, v102, v103
	v_add_f32_e32 v15, v98, v15
	v_add_f32_e32 v15, v99, v15
	s_waitcnt lgkmcnt(2)
	v_mfma_f32_32x32x16_bf16 v[16:31], v[194:197], v[198:201], v[16:31]
	v_sub_f32_e32 v104, v104, v14
	v_add_f32_e32 v15, v100, v15
	v_exp_f32_e32 v104, v104
	v_sub_f32_e32 v105, v105, v14
	v_sub_f32_e32 v106, v106, v14
	v_sub_f32_e32 v107, v107, v14
	v_sub_f32_e32 v108, v108, v14
	s_waitcnt lgkmcnt(0)
	v_mfma_f32_32x32x16_bf16 v[32:47], v[202:205], v[198:201], v[32:47]
	v_sub_f32_e32 v109, v109, v14
	v_sub_f32_e32 v110, v110, v14
	v_sub_f32_e32 v111, v111, v14
	v_add_f32_e32 v15, v101, v15
	v_exp_f32_e32 v105, v105
	v_exp_f32_e32 v106, v106
	v_exp_f32_e32 v107, v107
	v_exp_f32_e32 v108, v108
	v_exp_f32_e32 v109, v109
	v_exp_f32_e32 v110, v110
	ds_read_b64_tr_b16 v[194:195], v193 offset:48128
	ds_read_b64_tr_b16 v[196:197], v193 offset:49664
	v_exp_f32_e32 v111, v111
	ds_read_b64_tr_b16 v[204:205], v193 offset:49728
	ds_read_b64_tr_b16 v[202:203], v193 offset:48192
	v_add_f32_e32 v15, v102, v15
	v_add_f32_e32 v15, v103, v15
	v_add_f32_e32 v15, v104, v15
	v_cvt_pk_bf16_f32 v198, v104, v105
	v_cvt_pk_bf16_f32 v199, v106, v107
	v_cvt_pk_bf16_f32 v200, v108, v109
	v_cvt_pk_bf16_f32 v201, v110, v111
	v_add_f32_e32 v15, v105, v15
	v_add_f32_e32 v15, v106, v15
	s_waitcnt lgkmcnt(2)
	v_mfma_f32_32x32x16_bf16 v[16:31], v[194:197], v[198:201], v[16:31]
	v_add_f32_e32 v15, v107, v15
	v_add_f32_e32 v15, v108, v15
	v_add_f32_e32 v15, v109, v15
	v_add_f32_e32 v15, v110, v15
	v_add_f32_e32 v15, v111, v15
	v_fmac_f32_e32 v15, v190, v0
	v_mov_b32_e32 v193, v14
	s_waitcnt lgkmcnt(0)
	v_mfma_f32_32x32x16_bf16 v[32:47], v[202:205], v[198:201], v[32:47]
	v_mov_b32_e32 v190, v15

.LBB0_488:
	v_max_f32_e32 v0, v49, v49
	v_max_f32_e32 v14, v48, v48
	v_max_f32_e32 v0, v14, v0
	v_max3_f32 v0, v0, v50, v51
	v_max3_f32 v0, v0, v52, v53
	v_max3_f32 v0, v0, v54, v55
	v_max3_f32 v0, v0, v56, v57
	v_max3_f32 v0, v0, v58, v59
	v_max3_f32 v0, v0, v60, v61
	v_max3_f32 v0, v0, v62, v63
	v_max3_f32 v0, v0, v64, v65
	v_max3_f32 v0, v0, v66, v67
	v_max3_f32 v0, v0, v68, v69
	v_max3_f32 v0, v0, v70, v71
	v_max3_f32 v0, v0, v72, v73
	v_max3_f32 v0, v0, v74, v75
	v_max3_f32 v0, v0, v76, v77
	v_max3_f32 v0, v0, v78, v79
	v_mov_b32_e32 v14, v0
	v_mov_b32_e32 v15, v0
	s_nop 1
	v_permlane32_swap_b32_e32 v14, v15
	v_max3_f32 v14, v193, v14, v15
	v_sub_f32_e32 v0, v48, v14
	v_exp_f32_e32 v48, v0
	v_sub_f32_e32 v0, v49, v14
	v_exp_f32_e32 v49, v0
	v_sub_f32_e32 v0, v193, v14
	v_sub_f32_e32 v50, v50, v14
	v_sub_f32_e32 v51, v51, v14
	v_sub_f32_e32 v52, v52, v14
	v_sub_f32_e32 v53, v53, v14
	v_sub_f32_e32 v54, v54, v14
	v_sub_f32_e32 v55, v55, v14
	v_add_u32_e32 v193, v191, v192
	v_exp_f32_e32 v50, v50
	v_exp_f32_e32 v51, v51
	v_exp_f32_e32 v52, v52
	v_exp_f32_e32 v53, v53
	v_exp_f32_e32 v54, v54
	v_exp_f32_e32 v55, v55
	v_exp_f32_e32 v0, v0
	ds_read_b64_tr_b16 v[194:195], v193 offset:26624
	ds_read_b64_tr_b16 v[196:197], v193 offset:28160
	ds_read_b64_tr_b16 v[204:205], v193 offset:28224
	ds_read_b64_tr_b16 v[202:203], v193 offset:26688
	v_add_f32_e32 v15, 0, v48
	v_add_f32_e32 v15, v49, v15
	v_cmp_neq_f32_e32 vcc, 1.0, v0
	s_cbranch_vccz .Lnoresc_A
	v_mul_f32_e32 v30, v0, v30
	v_mul_f32_e32 v31, v0, v31
	v_mul_f32_e32 v28, v0, v28
	v_mul_f32_e32 v29, v0, v29
	v_mul_f32_e32 v26, v0, v26
	v_mul_f32_e32 v27, v0, v27
	v_mul_f32_e32 v24, v0, v24
	v_mul_f32_e32 v25, v0, v25
	v_mul_f32_e32 v22, v0, v22
	v_mul_f32_e32 v23, v0, v23
	v_mul_f32_e32 v20, v0, v20
	v_mul_f32_e32 v21, v0, v21
	v_mul_f32_e32 v18, v0, v18
	v_mul_f32_e32 v19, v0, v19
	v_mul_f32_e32 v16, v0, v16
	v_mul_f32_e32 v17, v0, v17
	v_mul_f32_e32 v46, v0, v46
	v_mul_f32_e32 v47, v0, v47
	v_mul_f32_e32 v44, v0, v44
	v_mul_f32_e32 v45, v0, v45
	v_mul_f32_e32 v42, v0, v42
	v_mul_f32_e32 v43, v0, v43
	v_mul_f32_e32 v40, v0, v40
	v_mul_f32_e32 v41, v0, v41
	v_mul_f32_e32 v38, v0, v38
	v_mul_f32_e32 v39, v0, v39
	v_mul_f32_e32 v36, v0, v36
	v_mul_f32_e32 v37, v0, v37
	v_mul_f32_e32 v34, v0, v34
	v_mul_f32_e32 v35, v0, v35
	v_mul_f32_e32 v32, v0, v32
	v_mul_f32_e32 v33, v0, v33
.Lnoresc_A:
	v_cvt_pk_bf16_f32 v198, v48, v49
	v_cvt_pk_bf16_f32 v199, v50, v51
	v_cvt_pk_bf16_f32 v200, v52, v53
	v_cvt_pk_bf16_f32 v201, v54, v55
	v_add_f32_e32 v15, v50, v15
	s_waitcnt lgkmcnt(2)
	v_mfma_f32_32x32x16_bf16 v[16:31], v[194:197], v[198:201], v[16:31]
	v_add_f32_e32 v15, v51, v15
	v_sub_f32_e32 v56, v56, v14
	v_add_f32_e32 v15, v52, v15
	v_exp_f32_e32 v56, v56
	v_sub_f32_e32 v57, v57, v14
	v_sub_f32_e32 v58, v58, v14
	v_sub_f32_e32 v59, v59, v14
	s_waitcnt lgkmcnt(0)
	v_mfma_f32_32x32x16_bf16 v[32:47], v[202:205], v[198:201], v[32:47]
	v_sub_f32_e32 v60, v60, v14
	v_sub_f32_e32 v61, v61, v14
	v_sub_f32_e32 v62, v62, v14
	v_sub_f32_e32 v63, v63, v14
	v_add_f32_e32 v15, v53, v15
	v_exp_f32_e32 v57, v57
	v_exp_f32_e32 v58, v58
	v_exp_f32_e32 v59, v59
	v_exp_f32_e32 v60, v60
	v_exp_f32_e32 v61, v61
	v_exp_f32_e32 v62, v62
	v_exp_f32_e32 v63, v63
	ds_read_b64_tr_b16 v[194:195], v193 offset:29696
	ds_read_b64_tr_b16 v[196:197], v193 offset:31232
	ds_read_b64_tr_b16 v[204:205], v193 offset:31296
	ds_read_b64_tr_b16 v[202:203], v193 offset:29760
	v_add_f32_e32 v15, v54, v15
	v_add_f32_e32 v15, v55, v15
	v_add_f32_e32 v15, v56, v15
	v_add_f32_e32 v15, v57, v15
	v_cvt_pk_bf16_f32 v198, v56, v57
	v_cvt_pk_bf16_f32 v199, v58, v59
	v_cvt_pk_bf16_f32 v200, v60, v61
	v_cvt_pk_bf16_f32 v201, v62, v63
	v_add_f32_e32 v15, v58, v15
	v_add_f32_e32 v15, v59, v15
	s_waitcnt lgkmcnt(2)
	v_mfma_f32_32x32x16_bf16 v[16:31], v[194:197], v[198:201], v[16:31]
	v_sub_f32_e32 v64, v64, v14
	v_add_f32_e32 v15, v60, v15
	v_exp_f32_e32 v64, v64
	v_sub_f32_e32 v65, v65, v14
	v_sub_f32_e32 v66, v66, v14
	v_sub_f32_e32 v67, v67, v14
	v_sub_f32_e32 v68, v68, v14
	s_waitcnt lgkmcnt(0)
	v_mfma_f32_32x32x16_bf16 v[32:47], v[202:205], v[198:201], v[32:47]
	v_sub_f32_e32 v69, v69, v14
	v_sub_f32_e32 v70, v70, v14
	v_sub_f32_e32 v71, v71, v14
	v_add_f32_e32 v15, v61, v15
	v_exp_f32_e32 v65, v65
	v_exp_f32_e32 v66, v66
	v_exp_f32_e32 v67, v67
	v_exp_f32_e32 v68, v68
	v_exp_f32_e32 v69, v69
	v_exp_f32_e32 v70, v70
	v_exp_f32_e32 v71, v71
	ds_read_b64_tr_b16 v[194:195], v193 offset:32768
	ds_read_b64_tr_b16 v[196:197], v193 offset:34304
	ds_read_b64_tr_b16 v[204:205], v193 offset:34368
	ds_read_b64_tr_b16 v[202:203], v193 offset:32832
	v_add_f32_e32 v15, v62, v15
	v_add_f32_e32 v15, v63, v15
	v_add_f32_e32 v15, v64, v15
	v_add_f32_e32 v15, v65, v15
	v_cvt_pk_bf16_f32 v198, v64, v65
	v_cvt_pk_bf16_f32 v199, v66, v67
	v_cvt_pk_bf16_f32 v200, v68, v69
	v_cvt_pk_bf16_f32 v201, v70, v71
	v_add_f32_e32 v15, v66, v15
	v_add_f32_e32 v15, v67, v15
	s_waitcnt lgkmcnt(2)
	v_mfma_f32_32x32x16_bf16 v[16:31], v[194:197], v[198:201], v[16:31]
	v_sub_f32_e32 v72, v72, v14
	v_add_f32_e32 v15, v68, v15
	v_exp_f32_e32 v72, v72
	v_sub_f32_e32 v73, v73, v14
	v_sub_f32_e32 v74, v74, v14
	v_sub_f32_e32 v75, v75, v14
	v_sub_f32_e32 v76, v76, v14
	s_waitcnt lgkmcnt(0)
	v_mfma_f32_32x32x16_bf16 v[32:47], v[202:205], v[198:201], v[32:47]
	v_sub_f32_e32 v77, v77, v14
	v_sub_f32_e32 v78, v78, v14
	v_sub_f32_e32 v79, v79, v14
	v_add_f32_e32 v15, v69, v15
	v_exp_f32_e32 v73, v73
	v_exp_f32_e32 v74, v74
	v_exp_f32_e32 v75, v75
	v_exp_f32_e32 v76, v76
	v_exp_f32_e32 v77, v77
	v_exp_f32_e32 v78, v78
	ds_read_b64_tr_b16 v[194:195], v193 offset:35840
	ds_read_b64_tr_b16 v[196:197], v193 offset:37376
	v_exp_f32_e32 v79, v79
	ds_read_b64_tr_b16 v[204:205], v193 offset:37440
	ds_read_b64_tr_b16 v[202:203], v193 offset:35904
	v_add_f32_e32 v15, v70, v15
	v_add_f32_e32 v15, v71, v15
	v_add_f32_e32 v15, v72, v15
	v_cvt_pk_bf16_f32 v198, v72, v73
	v_cvt_pk_bf16_f32 v199, v74, v75
	v_cvt_pk_bf16_f32 v200, v76, v77
	v_cvt_pk_bf16_f32 v201, v78, v79
	v_add_f32_e32 v15, v73, v15
	v_add_f32_e32 v15, v74, v15
	s_waitcnt lgkmcnt(2)
	v_mfma_f32_32x32x16_bf16 v[16:31], v[194:197], v[198:201], v[16:31]
	v_add_f32_e32 v15, v75, v15
	v_add_f32_e32 v15, v76, v15
	v_add_f32_e32 v15, v77, v15
	v_add_f32_e32 v15, v78, v15
	v_add_f32_e32 v15, v79, v15
	v_fmac_f32_e32 v15, v190, v0
	v_mov_b32_e32 v193, v14
	s_waitcnt lgkmcnt(0)
	v_mfma_f32_32x32x16_bf16 v[32:47], v[202:205], v[198:201], v[32:47]
	v_mov_b32_e32 v190, v15

	.amdhsa_kernel _Z14fwd_megakernel6Params
		.amdhsa_group_segment_fixed_size 78368
		.amdhsa_private_segment_fixed_size 0
		.amdhsa_kernarg_size 440
		.amdhsa_user_sgpr_count 2
		.amdhsa_user_sgpr_dispatch_ptr 0
		.amdhsa_user_sgpr_queue_ptr 0
		.amdhsa_user_sgpr_kernarg_segment_ptr 1
		.amdhsa_user_sgpr_dispatch_id 0
		.amdhsa_user_sgpr_kernarg_preload_length 0
		.amdhsa_user_sgpr_kernarg_preload_offset 0
		.amdhsa_user_sgpr_private_segment_size 0
		.amdhsa_uses_dynamic_stack 0
		.amdhsa_enable_private_segment 0
		.amdhsa_system_sgpr_workgroup_id_x 1
		.amdhsa_system_sgpr_workgroup_id_y 0
		.amdhsa_system_sgpr_workgroup_id_z 0
		.amdhsa_system_sgpr_workgroup_info 0
		.amdhsa_system_vgpr_workitem_id 2
		.amdhsa_next_free_vgpr 239
		.amdhsa_next_free_sgpr 101
		.amdhsa_accum_offset 240
		.amdhsa_reserve_vcc 1
		.amdhsa_float_round_mode_32 0
		.amdhsa_float_round_mode_16_64 0
		.amdhsa_float_denorm_mode_32 3
		.amdhsa_float_denorm_mode_16_64 3
		.amdhsa_dx10_clamp 1
		.amdhsa_ieee_mode 1
		.amdhsa_fp16_overflow 0
		.amdhsa_tg_split 0
		.amdhsa_exception_fp_ieee_invalid_op 0
		.amdhsa_exception_fp_denorm_src 0
		.amdhsa_exception_fp_ieee_div_zero 0
		.amdhsa_exception_fp_ieee_overflow 0
		.amdhsa_exception_fp_ieee_underflow 0
		.amdhsa_exception_fp_ieee_inexact 0
		.amdhsa_exception_int_div_zero 0
	.end_amdhsa_kernel

amdhsa.kernels:
  - .agpr_count:     0
    .args:
      - .offset:         0
        .size:           184
        .value_kind:     by_value
      - .offset:         184
        .size:           4
        .value_kind:     hidden_block_count_x
      - .offset:         188
        .size:           4
        .value_kind:     hidden_block_count_y
      - .offset:         192
        .size:           4
        .value_kind:     hidden_block_count_z
      - .offset:         196
        .size:           2
        .value_kind:     hidden_group_size_x
      - .offset:         198
        .size:           2
        .value_kind:     hidden_group_size_y
      - .offset:         200
        .size:           2
        .value_kind:     hidden_group_size_z
      - .offset:         202
        .size:           2
        .value_kind:     hidden_remainder_x
      - .offset:         204
        .size:           2
        .value_kind:     hidden_remainder_y
      - .offset:         206
        .size:           2
        .value_kind:     hidden_remainder_z
      - .offset:         224
        .size:           8
        .value_kind:     hidden_global_offset_x
      - .offset:         232
        .size:           8
        .value_kind:     hidden_global_offset_y
      - .offset:         240
        .size:           8
        .value_kind:     hidden_global_offset_z
      - .offset:         248
        .size:           2
        .value_kind:     hidden_grid_dims
      - .offset:         272
        .size:           8
        .value_kind:     hidden_multigrid_sync_arg
    .group_segment_fixed_size: 78368
    .kernarg_segment_align: 8
    .kernarg_segment_size: 440
    .language:       OpenCL C
    .language_version:
      - 2
      - 0
    .max_flat_workgroup_size: 256
    .name:           _Z14fwd_megakernel6Params
    .private_segment_fixed_size: 0
    .sgpr_count:     107
    .sgpr_spill_count: 165
    .symbol:         _Z14fwd_megakernel6Params.kd
    .uniform_work_group_size: 1
    .uses_dynamic_stack: false
    .vgpr_count:     239
    .vgpr_spill_count: 0
    .wavefront_size: 64
